# plain in-projection epilogue stores issued as global_ (vmcnt only) instead of flat_ (also lgkmcnt), so the next unit's LDS waits do not wait on them
# baseline (speedup 1.0000x reference)
.Lepip_plain:
	v_lshl_add_u32 v130, s6, 8, v150
	v_mov_b64_e32 v[128:129], s[8:9]
	v_mad_i64_i32 v[128:129], s[24:25], v130, s88, v[128:129]
	v_lshl_add_u64 v[128:129], v[148:149], 1, v[128:129]
	v_cvt_pk_bf16_f32 v120, v120, v121
	v_cvt_pk_bf16_f32 v121, v122, v123
	v_cvt_pk_bf16_f32 v122, v124, v125
	v_cvt_pk_bf16_f32 v123, v126, v127
	global_store_dwordx4 v[128:129], v[120:123], off sc1
	v_cvt_pk_bf16_f32 v112, v112, v113
	v_cvt_pk_bf16_f32 v113, v114, v115
	v_cvt_pk_bf16_f32 v114, v116, v117
	v_cvt_pk_bf16_f32 v115, v118, v119
	global_store_dwordx4 v[128:129], v[112:115], off offset:256 sc1
	s_mov_b64 s[24:25], 0x14000
	v_lshl_add_u64 v[130:131], s[24:25], 0, v[128:129]
	v_cvt_pk_bf16_f32 v104, v104, v105
	v_cvt_pk_bf16_f32 v105, v106, v107
	v_cvt_pk_bf16_f32 v106, v108, v109
	v_cvt_pk_bf16_f32 v107, v110, v111
	global_store_dwordx4 v[130:131], v[104:107], off sc1
	v_cvt_pk_bf16_f32 v96, v96, v97
	v_cvt_pk_bf16_f32 v97, v98, v99
	v_cvt_pk_bf16_f32 v98, v100, v101
	v_cvt_pk_bf16_f32 v99, v102, v103
	global_store_dwordx4 v[130:131], v[96:99], off offset:256 sc1
	s_mov_b64 s[24:25], 0x28000
	v_lshl_add_u64 v[130:131], s[24:25], 0, v[128:129]
	v_cvt_pk_bf16_f32 v88, v88, v89
	v_cvt_pk_bf16_f32 v89, v90, v91
	v_cvt_pk_bf16_f32 v90, v92, v93
	v_cvt_pk_bf16_f32 v91, v94, v95
	global_store_dwordx4 v[130:131], v[88:91], off sc1
	v_cvt_pk_bf16_f32 v80, v80, v81
	v_cvt_pk_bf16_f32 v81, v82, v83
	v_cvt_pk_bf16_f32 v82, v84, v85
	v_cvt_pk_bf16_f32 v83, v86, v87
	global_store_dwordx4 v[130:131], v[80:83], off offset:256 sc1
	s_mov_b64 s[24:25], 0x3c000
	v_lshl_add_u64 v[130:131], s[24:25], 0, v[128:129]
	v_cvt_pk_bf16_f32 v72, v72, v73
	v_cvt_pk_bf16_f32 v73, v74, v75
	v_cvt_pk_bf16_f32 v74, v76, v77
	v_cvt_pk_bf16_f32 v75, v78, v79
	global_store_dwordx4 v[130:131], v[72:75], off sc1
	v_cvt_pk_bf16_f32 v64, v64, v65
	v_cvt_pk_bf16_f32 v65, v66, v67
	v_cvt_pk_bf16_f32 v66, v68, v69
	v_cvt_pk_bf16_f32 v67, v70, v71
	global_store_dwordx4 v[130:131], v[64:67], off offset:256 sc1
	s_mov_b64 s[24:25], 0xa0000
	v_lshl_add_u64 v[130:131], s[24:25], 0, v[128:129]
	v_cvt_pk_bf16_f32 v56, v56, v57
	v_cvt_pk_bf16_f32 v57, v58, v59
	v_cvt_pk_bf16_f32 v58, v60, v61
	v_cvt_pk_bf16_f32 v59, v62, v63
	global_store_dwordx4 v[130:131], v[56:59], off sc1
	v_cvt_pk_bf16_f32 v48, v48, v49
	v_cvt_pk_bf16_f32 v49, v50, v51
	v_cvt_pk_bf16_f32 v50, v52, v53
	v_cvt_pk_bf16_f32 v51, v54, v55
	global_store_dwordx4 v[130:131], v[48:51], off offset:256 sc1
	s_mov_b64 s[24:25], 0xb4000
	v_lshl_add_u64 v[130:131], s[24:25], 0, v[128:129]
	v_cvt_pk_bf16_f32 v40, v40, v41
	v_cvt_pk_bf16_f32 v41, v42, v43
	v_cvt_pk_bf16_f32 v42, v44, v45
	v_cvt_pk_bf16_f32 v43, v46, v47
	global_store_dwordx4 v[130:131], v[40:43], off sc1
	v_cvt_pk_bf16_f32 v32, v32, v33
	v_cvt_pk_bf16_f32 v33, v34, v35
	v_cvt_pk_bf16_f32 v34, v36, v37
	v_cvt_pk_bf16_f32 v35, v38, v39
	global_store_dwordx4 v[130:131], v[32:35], off offset:256 sc1
	s_mov_b64 s[24:25], 0xc8000
	v_lshl_add_u64 v[130:131], s[24:25], 0, v[128:129]
	v_cvt_pk_bf16_f32 v24, v24, v25
	v_cvt_pk_bf16_f32 v25, v26, v27
	v_cvt_pk_bf16_f32 v26, v28, v29
	v_cvt_pk_bf16_f32 v27, v30, v31
	global_store_dwordx4 v[130:131], v[24:27], off sc1
	v_cvt_pk_bf16_f32 v16, v16, v17
	v_cvt_pk_bf16_f32 v17, v18, v19
	v_cvt_pk_bf16_f32 v18, v20, v21
	v_cvt_pk_bf16_f32 v19, v22, v23
	global_store_dwordx4 v[130:131], v[16:19], off offset:256 sc1
	s_mov_b64 s[24:25], 0xdc000
	v_lshl_add_u64 v[130:131], s[24:25], 0, v[128:129]
	v_cvt_pk_bf16_f32 v8, v8, v9
	v_cvt_pk_bf16_f32 v9, v10, v11
	v_cvt_pk_bf16_f32 v10, v12, v13
	v_cvt_pk_bf16_f32 v11, v14, v15
	global_store_dwordx4 v[130:131], v[8:11], off sc1
	v_cvt_pk_bf16_f32 v0, v0, v1
	v_cvt_pk_bf16_f32 v1, v2, v3
	v_cvt_pk_bf16_f32 v2, v4, v5
	v_cvt_pk_bf16_f32 v3, v6, v7
	global_store_dwordx4 v[130:131], v[0:3], off offset:256 sc1
	s_andn2_b64 vcc, exec, s[4:5]
	s_mov_b64 s[0:1], -1
	s_branch .Lepip_end
